# RES2 layer0: the partial third tile round (64 tiles) is split 8-way along K over all 512 WGs, partials added to x with f32 atomic adds
# baseline (speedup 1.0000x reference)
; DI int get_tid() { int t = threadIdx.x; asm volatile("" : "+v"(t)); return t; }
; template <int EPI>
; DI void gemm_phase(const Params& p, int layer, const bf16_t* __restrict__ A, int lda, const bf16_t* __restrict__ Bt, int ldb, int K, int MT, int NT,
;                    char* smem, bool rev = false) {
;   bf16_t* sA = (bf16_t*)smem;
;   bf16_t* sB = sA + 2 * 128 * LDT;
;   const int tid = get_tid(), lane = tid & 63, wave = tid >> 6, wr = wave >> 1, wc = wave & 1;
;   const int total = MT * NT;
;   int t = rev ? (int)(gridDim.x - 1 - blockIdx.x) : (int)blockIdx.x;
;   if (t >= total) return;
;   uint4 pa0, pa1, pa2, pa3, pb0, pb1, pb2, pb3, qa0, qa1, qa2, qa3, qb0, qb1, qb2, qb3;
;   const int lr = tid >> 3, lc = (tid & 7) * 8;
;   const int nk = K >> 6;
;   const int soff = lr * LDT + lc;
;   const int aoff = (wr * 64 + (lane & 31)) * LDT + (lane >> 5) * 8;
;   const int boff = (wc * 64 + (lane & 31)) * LDT + (lane >> 5) * 8;
;   int mt, nt; tile_map(t, MT, NT, mt, nt);
;   int m0 = mt * 128, n0 = nt * 128;
.Lmg_reenter:
	s_mov_b32 s52, s100
	s_mov_b32 s98, 0
	s_mov_b32 s99, 0
	s_mov_b32 s101, 0
	v_readlane_b32 s53, v255, 3
	s_nop 3
	v_and_b32_e32 v140, 63, v143
	v_lshrrev_b32_e32 v184, 6, v143
	v_and_b32_e32 v227, 31, v143
	v_bfe_u32 v228, v143, 5, 1
	v_readfirstlane_b32 s77, v184
	s_nop 3
	s_lshr_b32 s78, s77, 1
	s_and_b32 s79, s77, 1
	s_mul_i32 s80, s77, 0x1800
	v_readlane_b32 s66, v255, 0
	s_mov_b32 s65, s26
	s_cmp_eq_u32 s52, 5
	s_cbranch_scc0 .Lmg_norev_1
	s_and_b32 s0, s66, 7
	s_lshr_b32 s1, s66, 3
	s_lshr_b32 s10, s65, 3
	s_sub_u32 s10, s10, 1
	s_sub_u32 s1, s10, s1
	s_lshl_b32 s1, s1, 3
	s_add_u32 s66, s0, s1

; DI int get_tid() { int t = threadIdx.x; asm volatile("" : "+v"(t)); return t; }
; template <int EPI>
; DI void gemm_phase(const Params& p, int layer, const bf16_t* __restrict__ A, int lda, const bf16_t* __restrict__ Bt, int ldb, int K, int MT, int NT,
;                    char* smem, bool rev = false) {
;     ...
;   const int tid = get_tid(), lane = tid & 63, wave = tid >> 6, wr = wave >> 1, wc = wave & 1;
;   const int total = MT * NT;
;   int t = rev ? (int)(gridDim.x - 1 - blockIdx.x) : (int)blockIdx.x;
;   if (t >= total) return;
;   uint4 pa0, pa1, pa2, pa3, pb0, pb1, pb2, pb3, qa0, qa1, qa2, qa3, qb0, qb1, qb2, qb3;
;   const int lr = tid >> 3, lc = (tid & 7) * 8;
;   const int nk = K >> 6;
;   const int soff = lr * LDT + lc;
;   const int aoff = (wr * 64 + (lane & 31)) * LDT + (lane >> 5) * 8;
;   const int boff = (wc * 64 + (lane & 31)) * LDT + (lane >> 5) * 8;
;   int mt, nt; tile_map(t, MT, NT, mt, nt);
;   int m0 = mt * 128, n0 = nt * 128;
.Lmg_tile:
	s_cmp_eq_u32 s52, 3
	s_cbranch_scc0 .Lmg_nosk_10
	s_cmp_eq_u32 s101, 0
	s_cbranch_scc0 .Lmg_nosk_10
	s_lshl_b32 s0, s65, 1
	s_cmp_ge_u32 s66, s0
	s_cbranch_scc0 .Lmg_nosk_10
	s_cmp_le_u32 s64, s0
	s_cbranch_scc1 .Lmg_nosk_10
	s_sub_u32 s1, s64, s0
	s_lshl_b32 s1, s1, 3
	s_cmp_eq_u32 s1, s65
	s_cbranch_scc0 .Lmg_nosk_10
	s_sub_u32 s10, s66, s0
	s_and_b32 s11, s10, 7
	s_lshr_b32 s10, s10, 3
	s_add_u32 s66, s0, s10
	s_lshr_b32 s60, s60, 3
	s_mul_i32 s12, s11, s60
	s_mul_i32 s98, s12, s81
	s_mul_i32 s99, s12, s48
	s_mov_b32 s101, 1

; template <int EPI>
; DI void gemm_phase(const Params& p, int layer, const bf16_t* __restrict__ A, int lda, const bf16_t* __restrict__ Bt, int ldb, int K, int MT, int NT,
;                    char* smem, bool rev = false) {
;     ...
;   int mt, nt; tile_map(t, MT, NT, mt, nt);
;   int m0 = mt * 128, n0 = nt * 128;
;   const bf16_t* Agl = A + (size_t)(m0 + lr) * lda + lc;
;   const bf16_t* Bgl = Bt + (size_t)(n0 + lr) * ldb + lc;
;     ...
;   G_LOAD(p, 0)
;   G_LOAD(q, 64)
;   for (;;) {
;     G_WRITE(p, 0)
;     __syncthreads();
;     if (nk > 2) G_LOAD(p, 128)
;     f32x16 acc[2][2];
; #pragma unroll
;     for (int i = 0; i < 2; ++i)
; #pragma unroll
;       for (int j = 0; j < 2; ++j)
; #pragma unroll
;         for (int r = 0; r < 16; ++r) acc[i][j][r] = 0.f;
;     for (int kt = 0; kt < nk; kt += 2) {
;       G_COMPUTE(0)
;       G_WRITE(q, 1)
;       __syncthreads();
;       if (kt + 3 < nk) G_LOAD(q, (kt + 3) << 6)
;       G_COMPUTE(1)
.Lmg_tm_11:
	s_lshl_b32 s28, s61, 3
	s_mul_i32 s28, s28, s10
	s_sub_u32 s28, s1, s28
	s_mul_i32 s29, s28, s13
	s_lshr_b32 s29, s29, 16
	s_mul_i32 s44, s29, s12
	s_sub_u32 s44, s28, s44
	s_mul_i32 s0, s0, s61
	s_add_u32 s0, s0, s29
	s_lshl_b32 s10, s10, 3
	s_add_u32 s10, s10, s44
	s_lshl_b32 s67, s0, 8
	s_lshl_b32 s68, s10, 7
	s_mul_i32 s0, s67, s58
	s_add_u32 s70, s54, s0
	s_addc_u32 s71, s55, 0
	s_mul_i32 s0, s68, s59
	s_add_u32 s72, s56, s0
	s_addc_u32 s73, s57, 0
	s_add_u32 s70, s70, s98
	s_addc_u32 s71, s71, 0
	s_add_u32 s72, s72, s99
	s_addc_u32 s73, s73, 0
	s_barrier
	s_mov_b32 s74, s80
	s_mov_b32 m0, s74
	s_nop 0
	global_load_lds_dwordx4 v213, s[70:71] offset:0
	global_load_lds_dwordx4 v214, s[70:71] offset:1024
	global_load_lds_dwordx4 v215, s[70:71] offset:2048
	global_load_lds_dwordx4 v216, s[70:71] offset:3072
	s_add_u32 m0, s74, 0x1000
	s_nop 0
	global_load_lds_dwordx4 v217, s[72:73] offset:0
	global_load_lds_dwordx4 v218, s[72:73] offset:1024
	s_add_u32 s70, s70, s81
	s_addc_u32 s71, s71, 0
	s_add_u32 s72, s72, s48
	s_addc_u32 s73, s73, 0
	s_add_u32 s74, s80, 0x6000
	s_mov_b32 m0, s74
	s_nop 0
	global_load_lds_dwordx4 v213, s[70:71] offset:0
	global_load_lds_dwordx4 v214, s[70:71] offset:1024
	global_load_lds_dwordx4 v215, s[70:71] offset:2048
	global_load_lds_dwordx4 v216, s[70:71] offset:3072
	s_add_u32 m0, s74, 0x1000
	s_nop 0
	global_load_lds_dwordx4 v217, s[72:73] offset:0
	global_load_lds_dwordx4 v218, s[72:73] offset:1024
	s_add_u32 s70, s70, s81
	s_addc_u32 s71, s71, 0
	s_add_u32 s72, s72, s48
	s_addc_u32 s73, s73, 0
	s_add_u32 s74, s80, 0xc000
	s_mov_b32 s75, 0
	v_mov_b32_e32 v223, v219
	v_mov_b32_e32 v225, v221
	v_mov_b32_e32 v224, v220
	v_mov_b32_e32 v226, v222
	s_sub_u32 s76, s60, 3
	s_waitcnt vmcnt(6)
	s_barrier
	ds_read_b128 v[128:131], v225
	ds_read_b128 v[132:135], v225 offset:6144
	ds_read_b128 v[144:147], v223
	ds_read_b128 v[148:151], v223 offset:2048
	ds_read_b128 v[152:155], v223 offset:6144
	ds_read_b128 v[156:159], v223 offset:8192
	ds_read_b128 v[160:163], v226
	ds_read_b128 v[164:167], v226 offset:6144
	ds_read_b128 v[168:171], v224
	ds_read_b128 v[172:175], v224 offset:2048
	ds_read_b128 v[176:179], v224 offset:6144
	ds_read_b128 v[180:183], v224 offset:8192
	s_add_u32 s75, s75, 0x6000
	s_cmp_eq_u32 s75, 0x12000
	s_cselect_b32 s75, 0, s75
	s_mov_b32 m0, s74
	s_waitcnt lgkmcnt(9)
	v_mfma_f32_32x32x16_bf16 v[0:15], v[144:147], v[128:131], 0
	v_mfma_f32_32x32x16_bf16 v[16:31], v[144:147], v[132:135], 0
	global_load_lds_dwordx4 v213, s[70:71] offset:0
	s_waitcnt lgkmcnt(8)
	v_mfma_f32_32x32x16_bf16 v[32:47], v[148:151], v[128:131], 0
	v_mfma_f32_32x32x16_bf16 v[48:63], v[148:151], v[132:135], 0
	global_load_lds_dwordx4 v214, s[70:71] offset:1024
	s_waitcnt lgkmcnt(7)
	v_mfma_f32_32x32x16_bf16 v[64:79], v[152:155], v[128:131], 0
	v_mfma_f32_32x32x16_bf16 v[80:95], v[152:155], v[132:135], 0
	global_load_lds_dwordx4 v215, s[70:71] offset:2048
	s_waitcnt lgkmcnt(6)
	v_mfma_f32_32x32x16_bf16 v[96:111], v[156:159], v[128:131], 0
	v_mfma_f32_32x32x16_bf16 v[112:127], v[156:159], v[132:135], 0
	global_load_lds_dwordx4 v216, s[70:71] offset:3072
	s_add_u32 m0, s74, 0x1000
	s_waitcnt lgkmcnt(3)
	v_mfma_f32_32x32x16_bf16 v[0:15], v[168:171], v[160:163], v[0:15]
	v_mfma_f32_32x32x16_bf16 v[16:31], v[168:171], v[164:167], v[16:31]
	global_load_lds_dwordx4 v217, s[72:73] offset:0
	s_waitcnt lgkmcnt(2)
	v_mfma_f32_32x32x16_bf16 v[32:47], v[172:175], v[160:163], v[32:47]
	v_mfma_f32_32x32x16_bf16 v[48:63], v[172:175], v[164:167], v[48:63]
	global_load_lds_dwordx4 v218, s[72:73] offset:1024
	s_add_u32 s70, s70, s81
	s_addc_u32 s71, s71, 0
	s_add_u32 s72, s72, s48
	s_addc_u32 s73, s73, 0
	s_waitcnt lgkmcnt(1)
	v_mfma_f32_32x32x16_bf16 v[64:79], v[176:179], v[160:163], v[64:79]
	v_mfma_f32_32x32x16_bf16 v[80:95], v[176:179], v[164:167], v[80:95]
	v_add_u32_e32 v223, s75, v219
	v_add_u32_e32 v225, s75, v221
	v_add_u32_e32 v224, s75, v220
	v_add_u32_e32 v226, s75, v222
	s_waitcnt lgkmcnt(0)
	v_mfma_f32_32x32x16_bf16 v[96:111], v[180:183], v[160:163], v[96:111]
	v_mfma_f32_32x32x16_bf16 v[112:127], v[180:183], v[164:167], v[112:127]
	s_add_u32 s74, s74, 0x6000
	s_sub_u32 s1, s74, 0x12000
	s_add_u32 s0, s80, 0x12000
	s_cmp_ge_u32 s74, s0
	s_cselect_b32 s74, s1, s74

; DI unsigned pack2(float lo, float hi) { f32x2_t v = {lo, hi}; bf16x2_t r = __builtin_convertvector(v, bf16x2_t); return __builtin_bit_cast(unsigned, r); }
; template <int EPI>
; DI void epilogue(const Params& p, int layer, f32x16 (&acc)[2][2], int mrow0, int ncol0, int lane) {
;     ...
;   if (EPI == EPI_U) {
;     if (ncol0 < 768 && mrow0 < NLAT) {
;       bf16_t* HT = (bf16_t*)(p.ws + OFF_HT);
; #pragma unroll
;       for (int ni = 0; ni < 2; ++ni) {
;         const int col = ncol0 + ni * 32 + c, which = col >> 8, ch = col & 255;
; #pragma unroll
;         for (int mi = 0; mi < 2; ++mi)
; #pragma unroll
;           for (int g = 0; g < 4; ++g) {
;             const int row0 = mrow0 + mi * 32 + 8 * g + 4 * h, bq = row0 >> 12, s0 = row0 & 4095;
;             uint2 w;
;             w.x = pack2(acc[mi][ni][4 * g], acc[mi][ni][4 * g + 1]);
;             w.y = pack2(acc[mi][ni][4 * g + 2], acc[mi][ni][4 * g + 3]);
;             *(uint2*)(HT + (((size_t)which * NB + bq) * 256 + ch) * SEQ + s0) = w;
.Lmg_dbg_epi:
	s_nop 15
	s_nop 3
	s_cmp_eq_u32 s101, 1
	s_cbranch_scc1 .Lmg_epi_at
	s_cmp_eq_u32 s52, 1
	s_cbranch_scc1 .Lmg_epi1
	s_cmp_eq_u32 s52, 2
	s_cbranch_scc1 .Lmg_epi2
	s_cmp_eq_u32 s52, 3
	s_cbranch_scc1 .Lmg_epi3
	s_cmp_eq_u32 s52, 4
	s_cbranch_scc1 .Lmg_epi4
	s_cmp_eq_u32 s52, 5
	s_cbranch_scc1 .Lmg_epi5
	s_lshl_b32 s90, s78, 7
	s_add_u32 s90, s90, s67
	s_lshl_b32 s91, s79, 6
	s_add_u32 s91, s91, s68
	s_cmp_lt_u32 s91, 768
	s_cbranch_scc0 .Lmg_uvgt_13
	s_cmp_lt_u32 s67, 0x8000
	s_cbranch_scc0 .Lmg_uplain_12
	s_lshr_b32 s0, s91, 8
	s_lshl_b32 s0, s0, 3
	s_lshr_b32 s1, s67, 12
	s_add_u32 s0, s0, s1
	s_lshl_b32 s0, s0, 21
	s_add_u32 s0, s0, 0x12980000
	s_add_u32 s82, s24, s0
	s_addc_u32 s83, s25, 0
	s_and_b32 s10, s91, 255
	s_and_b32 s11, s67, 0xfff
	s_lshl_b32 s12, s78, 7
	s_add_u32 s11, s11, s12
	s_movk_i32 s13, 0x2000
	s_branch .Lmg_utr_14

; #define RES_LD(X, mi_, ni_) { _Pragma("unroll") for (int r = 0; r < 16; ++r) X[r] = xo_base[(size_t)((mi_) * 32 + crow(r, h)) * D + (ni_) * 32]; }
; #define RES_ST(X, mi_, ni_) { _Pragma("unroll") for (int r = 0; r < 16; ++r) xn_base[(size_t)((mi_) * 32 + crow(r, h)) * D + (ni_) * 32] = X[r] + gate[ni_] * acc[mi_][ni_][r]; }
; template <int EPI>
; DI void epilogue(const Params& p, int layer, f32x16 (&acc)[2][2], int mrow0, int ncol0, int lane) {
;     ...
;     const float* mod = (const float*)(p.ws + OFF_MOD) + (size_t)layer * 9 * 6144;
;     const int b9 = mrow0 < NLAT ? (mrow0 >> 12) : 8;
;     const int gsel = (EPI == EPI_RES1) ? 2 : 5;
;     const bool first = (EPI == EPI_RES1) && layer == 0;
;     const float* xo_base = xold_ptr(p, layer, first, mrow0) + (ncol0 + c);
;     float* xn_base = xnew_ptr(p, mrow0) + (ncol0 + c);
;     float gate[2];
; #pragma unroll
;     for (int ni = 0; ni < 2; ++ni) gate[ni] = mod[b9 * 6144 + gsel * 1024 + ncol0 + ni * 32 + c];
;     float xa[16], xb[16];
;     ...
;     RES_LD(xa, 0, 0)
;     RES_LD(xb, 0, 1)
;     RES_ST(xa, 0, 0)
;     RES_LD(xa, 1, 0)
;     RES_ST(xb, 0, 1)
;     RES_LD(xb, 1, 1)
;     RES_ST(xa, 1, 0)
;     RES_ST(xb, 1, 1)
.Lmg_rnf_19:
	s_mul_i32 s12, s53, 9
	s_add_u32 s12, s12, s1
	s_mul_i32 s12, s12, 6144
	s_lshl_b32 s11, s11, 10
	s_add_u32 s12, s12, s11
	s_add_u32 s12, s12, s91
	s_lshl_b32 s12, s12, 2
	s_add_u32 s12, s12, 0x1d300000
	s_add_u32 s86, s24, s12
	s_addc_u32 s87, s25, 0
	v_lshlrev_b32_e32 v184, 2, v227
	global_load_dword v229, v184, s[86:87]
	global_load_dword v230, v184, s[86:87] offset:128
	v_lshl_add_u32 v185, v228, 2, s0
	v_lshlrev_b32_e32 v185, 10, v185
	v_add3_u32 v185, v185, s91, v227
	v_lshlrev_b32_e32 v231, 2, v185
	s_waitcnt lgkmcnt(0)
	v_mov_b32_e32 v144, v231
	v_add_u32_e32 v145, 0x1000, v231
	v_add_u32_e32 v146, 0x2000, v231
	v_add_u32_e32 v147, 0x3000, v231
	v_add_u32_e32 v148, 0x8000, v231
	v_add_u32_e32 v149, 0x9000, v231
	v_add_u32_e32 v150, 0xa000, v231
	v_add_u32_e32 v151, 0xb000, v231
	v_add_u32_e32 v152, 0x10000, v231
	v_add_u32_e32 v153, 0x11000, v231
	v_add_u32_e32 v154, 0x12000, v231
	v_add_u32_e32 v155, 0x13000, v231
	v_add_u32_e32 v156, 0x18000, v231
	v_add_u32_e32 v157, 0x19000, v231
	v_add_u32_e32 v158, 0x1a000, v231
	v_add_u32_e32 v159, 0x1b000, v231
	global_load_dword v237, v144, s[84:85]
	global_load_dword v238, v145, s[84:85]
	global_load_dword v239, v146, s[84:85]
	global_load_dword v240, v147, s[84:85]
	global_load_dword v241, v148, s[84:85]
	global_load_dword v242, v149, s[84:85]
	global_load_dword v243, v150, s[84:85]
	global_load_dword v244, v151, s[84:85]
	global_load_dword v245, v152, s[84:85]
	global_load_dword v246, v153, s[84:85]
	global_load_dword v247, v154, s[84:85]
	global_load_dword v248, v155, s[84:85]
	global_load_dword v249, v156, s[84:85]
	global_load_dword v250, v157, s[84:85]
	global_load_dword v251, v158, s[84:85]
	global_load_dword v252, v159, s[84:85]
	global_load_dword v176, v144, s[84:85] offset:128
	global_load_dword v177, v145, s[84:85] offset:128
	global_load_dword v178, v146, s[84:85] offset:128
	global_load_dword v179, v147, s[84:85] offset:128
	global_load_dword v180, v148, s[84:85] offset:128
	global_load_dword v181, v149, s[84:85] offset:128
	global_load_dword v182, v150, s[84:85] offset:128
	global_load_dword v183, v151, s[84:85] offset:128
	global_load_dword v184, v152, s[84:85] offset:128
	global_load_dword v185, v153, s[84:85] offset:128
	global_load_dword v186, v154, s[84:85] offset:128
	global_load_dword v187, v155, s[84:85] offset:128
	global_load_dword v128, v156, s[84:85] offset:128
	global_load_dword v129, v157, s[84:85] offset:128
	global_load_dword v130, v158, s[84:85] offset:128
	global_load_dword v131, v159, s[84:85] offset:128
	v_add_u32_e32 v160, 0x20000, v231
	v_add_u32_e32 v161, 0x21000, v231
	v_add_u32_e32 v162, 0x22000, v231
	v_add_u32_e32 v163, 0x23000, v231
	v_add_u32_e32 v164, 0x28000, v231
	v_add_u32_e32 v165, 0x29000, v231
	v_add_u32_e32 v166, 0x2a000, v231
	v_add_u32_e32 v167, 0x2b000, v231
	v_add_u32_e32 v168, 0x30000, v231
	v_add_u32_e32 v169, 0x31000, v231
	v_add_u32_e32 v170, 0x32000, v231
	v_add_u32_e32 v171, 0x33000, v231
	v_add_u32_e32 v172, 0x38000, v231
	v_add_u32_e32 v173, 0x39000, v231
	v_add_u32_e32 v174, 0x3a000, v231
	v_add_u32_e32 v175, 0x3b000, v231
	s_waitcnt vmcnt(16)
	v_fmac_f32_e32 v237, v229, v0
	v_fmac_f32_e32 v238, v229, v1
	v_fmac_f32_e32 v239, v229, v2
	v_fmac_f32_e32 v240, v229, v3
	v_fmac_f32_e32 v241, v229, v4
	v_fmac_f32_e32 v242, v229, v5
	v_fmac_f32_e32 v243, v229, v6
	v_fmac_f32_e32 v244, v229, v7
	v_fmac_f32_e32 v245, v229, v8
	v_fmac_f32_e32 v246, v229, v9
	v_fmac_f32_e32 v247, v229, v10
	v_fmac_f32_e32 v248, v229, v11
	v_fmac_f32_e32 v249, v229, v12
	v_fmac_f32_e32 v250, v229, v13
	v_fmac_f32_e32 v251, v229, v14
	v_fmac_f32_e32 v252, v229, v15
	global_store_dword v144, v237, s[82:83]
	global_store_dword v145, v238, s[82:83]
	global_store_dword v146, v239, s[82:83]
	global_store_dword v147, v240, s[82:83]
	global_store_dword v148, v241, s[82:83]
	global_store_dword v149, v242, s[82:83]
	global_store_dword v150, v243, s[82:83]
	global_store_dword v151, v244, s[82:83]
	global_store_dword v152, v245, s[82:83]
	global_store_dword v153, v246, s[82:83]
	global_store_dword v154, v247, s[82:83]
	global_store_dword v155, v248, s[82:83]
	global_store_dword v156, v249, s[82:83]
	global_store_dword v157, v250, s[82:83]
	global_store_dword v158, v251, s[82:83]
	global_store_dword v159, v252, s[82:83]
	global_load_dword v237, v160, s[84:85]
	global_load_dword v238, v161, s[84:85]
	global_load_dword v239, v162, s[84:85]
	global_load_dword v240, v163, s[84:85]
	global_load_dword v241, v164, s[84:85]
	global_load_dword v242, v165, s[84:85]
	global_load_dword v243, v166, s[84:85]
	global_load_dword v244, v167, s[84:85]
	global_load_dword v245, v168, s[84:85]
	global_load_dword v246, v169, s[84:85]
	global_load_dword v247, v170, s[84:85]
	global_load_dword v248, v171, s[84:85]
	global_load_dword v249, v172, s[84:85]
	global_load_dword v250, v173, s[84:85]
	global_load_dword v251, v174, s[84:85]
	global_load_dword v252, v175, s[84:85]
	s_waitcnt vmcnt(32)
; #define RES_LD(X, mi_, ni_) { _Pragma("unroll") for (int r = 0; r < 16; ++r) X[r] = xo_base[(size_t)((mi_) * 32 + crow(r, h)) * D + (ni_) * 32]; }
; #define RES_ST(X, mi_, ni_) { _Pragma("unroll") for (int r = 0; r < 16; ++r) xn_base[(size_t)((mi_) * 32 + crow(r, h)) * D + (ni_) * 32] = X[r] + gate[ni_] * acc[mi_][ni_][r]; }
; template <int EPI>
; DI void epilogue(const Params& p, int layer, f32x16 (&acc)[2][2], int mrow0, int ncol0, int lane) {
;     ...
;     RES_LD(xa, 0, 0)
;     RES_LD(xb, 0, 1)
;     RES_ST(xa, 0, 0)
;     RES_LD(xa, 1, 0)
;     RES_ST(xb, 0, 1)
;     RES_LD(xb, 1, 1)
;     RES_ST(xa, 1, 0)
;     RES_ST(xb, 1, 1)
	v_fmac_f32_e32 v176, v230, v16
	v_fmac_f32_e32 v177, v230, v17
	v_fmac_f32_e32 v178, v230, v18
	v_fmac_f32_e32 v179, v230, v19
	v_fmac_f32_e32 v180, v230, v20
	v_fmac_f32_e32 v181, v230, v21
	v_fmac_f32_e32 v182, v230, v22
	v_fmac_f32_e32 v183, v230, v23
	v_fmac_f32_e32 v184, v230, v24
	v_fmac_f32_e32 v185, v230, v25
	v_fmac_f32_e32 v186, v230, v26
	v_fmac_f32_e32 v187, v230, v27
	v_fmac_f32_e32 v128, v230, v28
	v_fmac_f32_e32 v129, v230, v29
	v_fmac_f32_e32 v130, v230, v30
	v_fmac_f32_e32 v131, v230, v31
	global_store_dword v144, v176, s[82:83] offset:128
	global_store_dword v145, v177, s[82:83] offset:128
	global_store_dword v146, v178, s[82:83] offset:128
	global_store_dword v147, v179, s[82:83] offset:128
	global_store_dword v148, v180, s[82:83] offset:128
	global_store_dword v149, v181, s[82:83] offset:128
	global_store_dword v150, v182, s[82:83] offset:128
	global_store_dword v151, v183, s[82:83] offset:128
	global_store_dword v152, v184, s[82:83] offset:128
	global_store_dword v153, v185, s[82:83] offset:128
	global_store_dword v154, v186, s[82:83] offset:128
	global_store_dword v155, v187, s[82:83] offset:128
	global_store_dword v156, v128, s[82:83] offset:128
	global_store_dword v157, v129, s[82:83] offset:128
	global_store_dword v158, v130, s[82:83] offset:128
	global_store_dword v159, v131, s[82:83] offset:128
	global_load_dword v176, v160, s[84:85] offset:128
	global_load_dword v177, v161, s[84:85] offset:128
	global_load_dword v178, v162, s[84:85] offset:128
	global_load_dword v179, v163, s[84:85] offset:128
	global_load_dword v180, v164, s[84:85] offset:128
	global_load_dword v181, v165, s[84:85] offset:128
	global_load_dword v182, v166, s[84:85] offset:128
	global_load_dword v183, v167, s[84:85] offset:128
	global_load_dword v184, v168, s[84:85] offset:128
	global_load_dword v185, v169, s[84:85] offset:128
	global_load_dword v186, v170, s[84:85] offset:128
	global_load_dword v187, v171, s[84:85] offset:128
	global_load_dword v128, v172, s[84:85] offset:128
	global_load_dword v129, v173, s[84:85] offset:128
	global_load_dword v130, v174, s[84:85] offset:128
	global_load_dword v131, v175, s[84:85] offset:128
	v_add_u32_e32 v144, 0x40000, v231
	v_add_u32_e32 v145, 0x41000, v231
	v_add_u32_e32 v146, 0x42000, v231
	v_add_u32_e32 v147, 0x43000, v231
	v_add_u32_e32 v148, 0x48000, v231
	v_add_u32_e32 v149, 0x49000, v231
	v_add_u32_e32 v150, 0x4a000, v231
	v_add_u32_e32 v151, 0x4b000, v231
	v_add_u32_e32 v152, 0x50000, v231
	v_add_u32_e32 v153, 0x51000, v231
	v_add_u32_e32 v154, 0x52000, v231
	v_add_u32_e32 v155, 0x53000, v231
	v_add_u32_e32 v156, 0x58000, v231
	v_add_u32_e32 v157, 0x59000, v231
	v_add_u32_e32 v158, 0x5a000, v231
	v_add_u32_e32 v159, 0x5b000, v231
	s_waitcnt vmcnt(32)
	v_fmac_f32_e32 v237, v229, v32
	v_fmac_f32_e32 v238, v229, v33
	v_fmac_f32_e32 v239, v229, v34
	v_fmac_f32_e32 v240, v229, v35
	v_fmac_f32_e32 v241, v229, v36
	v_fmac_f32_e32 v242, v229, v37
	v_fmac_f32_e32 v243, v229, v38
	v_fmac_f32_e32 v244, v229, v39
	v_fmac_f32_e32 v245, v229, v40
	v_fmac_f32_e32 v246, v229, v41
	v_fmac_f32_e32 v247, v229, v42
	v_fmac_f32_e32 v248, v229, v43
	v_fmac_f32_e32 v249, v229, v44
	v_fmac_f32_e32 v250, v229, v45
	v_fmac_f32_e32 v251, v229, v46
	v_fmac_f32_e32 v252, v229, v47
	global_store_dword v160, v237, s[82:83]
	global_store_dword v161, v238, s[82:83]
	global_store_dword v162, v239, s[82:83]
	global_store_dword v163, v240, s[82:83]
	global_store_dword v164, v241, s[82:83]
	global_store_dword v165, v242, s[82:83]
	global_store_dword v166, v243, s[82:83]
	global_store_dword v167, v244, s[82:83]
	global_store_dword v168, v245, s[82:83]
	global_store_dword v169, v246, s[82:83]
	global_store_dword v170, v247, s[82:83]
	global_store_dword v171, v248, s[82:83]
	global_store_dword v172, v249, s[82:83]
	global_store_dword v173, v250, s[82:83]
	global_store_dword v174, v251, s[82:83]
	global_store_dword v175, v252, s[82:83]
	global_load_dword v237, v144, s[84:85]
	global_load_dword v238, v145, s[84:85]
	global_load_dword v239, v146, s[84:85]
	global_load_dword v240, v147, s[84:85]
	global_load_dword v241, v148, s[84:85]
	global_load_dword v242, v149, s[84:85]
	global_load_dword v243, v150, s[84:85]
	global_load_dword v244, v151, s[84:85]
	global_load_dword v245, v152, s[84:85]
	global_load_dword v246, v153, s[84:85]
	global_load_dword v247, v154, s[84:85]
	global_load_dword v248, v155, s[84:85]
	global_load_dword v249, v156, s[84:85]
	global_load_dword v250, v157, s[84:85]
	global_load_dword v251, v158, s[84:85]
	global_load_dword v252, v159, s[84:85]
	s_waitcnt vmcnt(32)
; #define RES_LD(X, mi_, ni_) { _Pragma("unroll") for (int r = 0; r < 16; ++r) X[r] = xo_base[(size_t)((mi_) * 32 + crow(r, h)) * D + (ni_) * 32]; }
; #define RES_ST(X, mi_, ni_) { _Pragma("unroll") for (int r = 0; r < 16; ++r) xn_base[(size_t)((mi_) * 32 + crow(r, h)) * D + (ni_) * 32] = X[r] + gate[ni_] * acc[mi_][ni_][r]; }
; template <int EPI>
; DI void epilogue(const Params& p, int layer, f32x16 (&acc)[2][2], int mrow0, int ncol0, int lane) {
;     ...
;     RES_LD(xa, 0, 0)
;     RES_LD(xb, 0, 1)
;     RES_ST(xa, 0, 0)
;     RES_LD(xa, 1, 0)
;     RES_ST(xb, 0, 1)
;     RES_LD(xb, 1, 1)
;     RES_ST(xa, 1, 0)
;     RES_ST(xb, 1, 1)
	v_fmac_f32_e32 v176, v230, v48
	v_fmac_f32_e32 v177, v230, v49
	v_fmac_f32_e32 v178, v230, v50
	v_fmac_f32_e32 v179, v230, v51
	v_fmac_f32_e32 v180, v230, v52
	v_fmac_f32_e32 v181, v230, v53
	v_fmac_f32_e32 v182, v230, v54
	v_fmac_f32_e32 v183, v230, v55
	v_fmac_f32_e32 v184, v230, v56
	v_fmac_f32_e32 v185, v230, v57
	v_fmac_f32_e32 v186, v230, v58
	v_fmac_f32_e32 v187, v230, v59
	v_fmac_f32_e32 v128, v230, v60
	v_fmac_f32_e32 v129, v230, v61
	v_fmac_f32_e32 v130, v230, v62
	v_fmac_f32_e32 v131, v230, v63
	global_store_dword v160, v176, s[82:83] offset:128
	global_store_dword v161, v177, s[82:83] offset:128
	global_store_dword v162, v178, s[82:83] offset:128
	global_store_dword v163, v179, s[82:83] offset:128
	global_store_dword v164, v180, s[82:83] offset:128
	global_store_dword v165, v181, s[82:83] offset:128
	global_store_dword v166, v182, s[82:83] offset:128
	global_store_dword v167, v183, s[82:83] offset:128
	global_store_dword v168, v184, s[82:83] offset:128
	global_store_dword v169, v185, s[82:83] offset:128
	global_store_dword v170, v186, s[82:83] offset:128
	global_store_dword v171, v187, s[82:83] offset:128
	global_store_dword v172, v128, s[82:83] offset:128
	global_store_dword v173, v129, s[82:83] offset:128
	global_store_dword v174, v130, s[82:83] offset:128
	global_store_dword v175, v131, s[82:83] offset:128
	global_load_dword v176, v144, s[84:85] offset:128
	global_load_dword v177, v145, s[84:85] offset:128
	global_load_dword v178, v146, s[84:85] offset:128
	global_load_dword v179, v147, s[84:85] offset:128
	global_load_dword v180, v148, s[84:85] offset:128
	global_load_dword v181, v149, s[84:85] offset:128
	global_load_dword v182, v150, s[84:85] offset:128
	global_load_dword v183, v151, s[84:85] offset:128
	global_load_dword v184, v152, s[84:85] offset:128
	global_load_dword v185, v153, s[84:85] offset:128
	global_load_dword v186, v154, s[84:85] offset:128
	global_load_dword v187, v155, s[84:85] offset:128
	global_load_dword v128, v156, s[84:85] offset:128
	global_load_dword v129, v157, s[84:85] offset:128
	global_load_dword v130, v158, s[84:85] offset:128
	global_load_dword v131, v159, s[84:85] offset:128
	v_add_u32_e32 v160, 0x60000, v231
	v_add_u32_e32 v161, 0x61000, v231
	v_add_u32_e32 v162, 0x62000, v231
	v_add_u32_e32 v163, 0x63000, v231
	v_add_u32_e32 v164, 0x68000, v231
	v_add_u32_e32 v165, 0x69000, v231
	v_add_u32_e32 v166, 0x6a000, v231
	v_add_u32_e32 v167, 0x6b000, v231
	v_add_u32_e32 v168, 0x70000, v231
	v_add_u32_e32 v169, 0x71000, v231
	v_add_u32_e32 v170, 0x72000, v231
	v_add_u32_e32 v171, 0x73000, v231
	v_add_u32_e32 v172, 0x78000, v231
	v_add_u32_e32 v173, 0x79000, v231
	v_add_u32_e32 v174, 0x7a000, v231
	v_add_u32_e32 v175, 0x7b000, v231
	s_waitcnt vmcnt(32)
	v_fmac_f32_e32 v237, v229, v64
	v_fmac_f32_e32 v238, v229, v65
	v_fmac_f32_e32 v239, v229, v66
	v_fmac_f32_e32 v240, v229, v67
	v_fmac_f32_e32 v241, v229, v68
	v_fmac_f32_e32 v242, v229, v69
	v_fmac_f32_e32 v243, v229, v70
	v_fmac_f32_e32 v244, v229, v71
	v_fmac_f32_e32 v245, v229, v72
	v_fmac_f32_e32 v246, v229, v73
	v_fmac_f32_e32 v247, v229, v74
	v_fmac_f32_e32 v248, v229, v75
	v_fmac_f32_e32 v249, v229, v76
	v_fmac_f32_e32 v250, v229, v77
	v_fmac_f32_e32 v251, v229, v78
	v_fmac_f32_e32 v252, v229, v79
	global_store_dword v144, v237, s[82:83]
	global_store_dword v145, v238, s[82:83]
	global_store_dword v146, v239, s[82:83]
	global_store_dword v147, v240, s[82:83]
	global_store_dword v148, v241, s[82:83]
	global_store_dword v149, v242, s[82:83]
	global_store_dword v150, v243, s[82:83]
	global_store_dword v151, v244, s[82:83]
	global_store_dword v152, v245, s[82:83]
	global_store_dword v153, v246, s[82:83]
	global_store_dword v154, v247, s[82:83]
	global_store_dword v155, v248, s[82:83]
	global_store_dword v156, v249, s[82:83]
	global_store_dword v157, v250, s[82:83]
	global_store_dword v158, v251, s[82:83]
	global_store_dword v159, v252, s[82:83]
	global_load_dword v237, v160, s[84:85]
	global_load_dword v238, v161, s[84:85]
	global_load_dword v239, v162, s[84:85]
	global_load_dword v240, v163, s[84:85]
	global_load_dword v241, v164, s[84:85]
	global_load_dword v242, v165, s[84:85]
	global_load_dword v243, v166, s[84:85]
	global_load_dword v244, v167, s[84:85]
	global_load_dword v245, v168, s[84:85]
	global_load_dword v246, v169, s[84:85]
	global_load_dword v247, v170, s[84:85]
	global_load_dword v248, v171, s[84:85]
	global_load_dword v249, v172, s[84:85]
	global_load_dword v250, v173, s[84:85]
	global_load_dword v251, v174, s[84:85]
	global_load_dword v252, v175, s[84:85]
	s_waitcnt vmcnt(32)
; #define RES_LD(X, mi_, ni_) { _Pragma("unroll") for (int r = 0; r < 16; ++r) X[r] = xo_base[(size_t)((mi_) * 32 + crow(r, h)) * D + (ni_) * 32]; }
; #define RES_ST(X, mi_, ni_) { _Pragma("unroll") for (int r = 0; r < 16; ++r) xn_base[(size_t)((mi_) * 32 + crow(r, h)) * D + (ni_) * 32] = X[r] + gate[ni_] * acc[mi_][ni_][r]; }
; template <int EPI>
; DI void epilogue(const Params& p, int layer, f32x16 (&acc)[2][2], int mrow0, int ncol0, int lane) {
;     ...
;     RES_LD(xa, 0, 0)
;     RES_LD(xb, 0, 1)
;     RES_ST(xa, 0, 0)
;     RES_LD(xa, 1, 0)
;     RES_ST(xb, 0, 1)
;     RES_LD(xb, 1, 1)
;     RES_ST(xa, 1, 0)
;     RES_ST(xb, 1, 1)
	v_fmac_f32_e32 v176, v230, v80
	v_fmac_f32_e32 v177, v230, v81
	v_fmac_f32_e32 v178, v230, v82
	v_fmac_f32_e32 v179, v230, v83
	v_fmac_f32_e32 v180, v230, v84
	v_fmac_f32_e32 v181, v230, v85
	v_fmac_f32_e32 v182, v230, v86
	v_fmac_f32_e32 v183, v230, v87
	v_fmac_f32_e32 v184, v230, v88
	v_fmac_f32_e32 v185, v230, v89
	v_fmac_f32_e32 v186, v230, v90
	v_fmac_f32_e32 v187, v230, v91
	v_fmac_f32_e32 v128, v230, v92
	v_fmac_f32_e32 v129, v230, v93
	v_fmac_f32_e32 v130, v230, v94
	v_fmac_f32_e32 v131, v230, v95
	global_store_dword v144, v176, s[82:83] offset:128
	global_store_dword v145, v177, s[82:83] offset:128
	global_store_dword v146, v178, s[82:83] offset:128
	global_store_dword v147, v179, s[82:83] offset:128
	global_store_dword v148, v180, s[82:83] offset:128
	global_store_dword v149, v181, s[82:83] offset:128
	global_store_dword v150, v182, s[82:83] offset:128
	global_store_dword v151, v183, s[82:83] offset:128
	global_store_dword v152, v184, s[82:83] offset:128
	global_store_dword v153, v185, s[82:83] offset:128
	global_store_dword v154, v186, s[82:83] offset:128
	global_store_dword v155, v187, s[82:83] offset:128
	global_store_dword v156, v128, s[82:83] offset:128
	global_store_dword v157, v129, s[82:83] offset:128
	global_store_dword v158, v130, s[82:83] offset:128
	global_store_dword v159, v131, s[82:83] offset:128
	global_load_dword v176, v160, s[84:85] offset:128
	global_load_dword v177, v161, s[84:85] offset:128
	global_load_dword v178, v162, s[84:85] offset:128
	global_load_dword v179, v163, s[84:85] offset:128
	global_load_dword v180, v164, s[84:85] offset:128
	global_load_dword v181, v165, s[84:85] offset:128
	global_load_dword v182, v166, s[84:85] offset:128
	global_load_dword v183, v167, s[84:85] offset:128
	global_load_dword v184, v168, s[84:85] offset:128
	global_load_dword v185, v169, s[84:85] offset:128
	global_load_dword v186, v170, s[84:85] offset:128
	global_load_dword v187, v171, s[84:85] offset:128
	global_load_dword v128, v172, s[84:85] offset:128
	global_load_dword v129, v173, s[84:85] offset:128
	global_load_dword v130, v174, s[84:85] offset:128
	global_load_dword v131, v175, s[84:85] offset:128
	s_waitcnt vmcnt(32)
	v_fmac_f32_e32 v237, v229, v96
	v_fmac_f32_e32 v238, v229, v97
	v_fmac_f32_e32 v239, v229, v98
	v_fmac_f32_e32 v240, v229, v99
	v_fmac_f32_e32 v241, v229, v100
	v_fmac_f32_e32 v242, v229, v101
	v_fmac_f32_e32 v243, v229, v102
	v_fmac_f32_e32 v244, v229, v103
	v_fmac_f32_e32 v245, v229, v104
	v_fmac_f32_e32 v246, v229, v105
	v_fmac_f32_e32 v247, v229, v106
	v_fmac_f32_e32 v248, v229, v107
	v_fmac_f32_e32 v249, v229, v108
	v_fmac_f32_e32 v250, v229, v109
	v_fmac_f32_e32 v251, v229, v110
	v_fmac_f32_e32 v252, v229, v111
	global_store_dword v160, v237, s[82:83]
	global_store_dword v161, v238, s[82:83]
	global_store_dword v162, v239, s[82:83]
	global_store_dword v163, v240, s[82:83]
	global_store_dword v164, v241, s[82:83]
	global_store_dword v165, v242, s[82:83]
	global_store_dword v166, v243, s[82:83]
	global_store_dword v167, v244, s[82:83]
	global_store_dword v168, v245, s[82:83]
	global_store_dword v169, v246, s[82:83]
	global_store_dword v170, v247, s[82:83]
	global_store_dword v171, v248, s[82:83]
	global_store_dword v172, v249, s[82:83]
	global_store_dword v173, v250, s[82:83]
	global_store_dword v174, v251, s[82:83]
	global_store_dword v175, v252, s[82:83]
	s_waitcnt vmcnt(16)
	v_fmac_f32_e32 v176, v230, v112
	v_fmac_f32_e32 v177, v230, v113
	v_fmac_f32_e32 v178, v230, v114
	v_fmac_f32_e32 v179, v230, v115
	v_fmac_f32_e32 v180, v230, v116
	v_fmac_f32_e32 v181, v230, v117
	v_fmac_f32_e32 v182, v230, v118
	v_fmac_f32_e32 v183, v230, v119
	v_fmac_f32_e32 v184, v230, v120
	v_fmac_f32_e32 v185, v230, v121
	v_fmac_f32_e32 v186, v230, v122
	v_fmac_f32_e32 v187, v230, v123
	v_fmac_f32_e32 v128, v230, v124
	v_fmac_f32_e32 v129, v230, v125
	v_fmac_f32_e32 v130, v230, v126
	v_fmac_f32_e32 v131, v230, v127
	global_store_dword v160, v176, s[82:83] offset:128
	global_store_dword v161, v177, s[82:83] offset:128
	global_store_dword v162, v178, s[82:83] offset:128
	global_store_dword v163, v179, s[82:83] offset:128
	global_store_dword v164, v180, s[82:83] offset:128
	global_store_dword v165, v181, s[82:83] offset:128
	global_store_dword v166, v182, s[82:83] offset:128
	global_store_dword v167, v183, s[82:83] offset:128
	global_store_dword v168, v184, s[82:83] offset:128
	global_store_dword v169, v185, s[82:83] offset:128
	global_store_dword v170, v186, s[82:83] offset:128
	global_store_dword v171, v187, s[82:83] offset:128
	global_store_dword v172, v128, s[82:83] offset:128
	global_store_dword v173, v129, s[82:83] offset:128
	global_store_dword v174, v130, s[82:83] offset:128
	global_store_dword v175, v131, s[82:83] offset:128
	s_branch .Lmg_next
.Lmg_epi_at:
	s_lshl_b32 s90, s78, 7
	s_add_u32 s90, s90, s67
	s_lshl_b32 s91, s79, 6
	s_add_u32 s91, s91, s68
	s_cmp_lt_u32 s67, 0x8000
	s_cbranch_scc1 .Lmg_rlat_21
	s_add_u32 s82, s24, 0x19d80000
	s_addc_u32 s83, s25, 0
	s_sub_u32 s0, s90, 0x8000
	s_mov_b32 s1, 8
	s_mov_b32 s10, 16
	s_branch .Lmg_rj_22

; #define RES_LD(X, mi_, ni_) { _Pragma("unroll") for (int r = 0; r < 16; ++r) X[r] = xo_base[(size_t)((mi_) * 32 + crow(r, h)) * D + (ni_) * 32]; }
; #define RES_ST(X, mi_, ni_) { _Pragma("unroll") for (int r = 0; r < 16; ++r) xn_base[(size_t)((mi_) * 32 + crow(r, h)) * D + (ni_) * 32] = X[r] + gate[ni_] * acc[mi_][ni_][r]; }
; template <int EPI>
; DI void epilogue(const Params& p, int layer, f32x16 (&acc)[2][2], int mrow0, int ncol0, int lane) {
;     ...
;     const float* mod = (const float*)(p.ws + OFF_MOD) + (size_t)layer * 9 * 6144;
;     const int b9 = mrow0 < NLAT ? (mrow0 >> 12) : 8;
;     const int gsel = (EPI == EPI_RES1) ? 2 : 5;
;     const bool first = (EPI == EPI_RES1) && layer == 0;
;     const float* xo_base = xold_ptr(p, layer, first, mrow0) + (ncol0 + c);
;     float* xn_base = xnew_ptr(p, mrow0) + (ncol0 + c);
;     float gate[2];
; #pragma unroll
;     for (int ni = 0; ni < 2; ++ni) gate[ni] = mod[b9 * 6144 + gsel * 1024 + ncol0 + ni * 32 + c];
;     float xa[16], xb[16];
;     ...
;     RES_LD(xa, 0, 0)
;     RES_LD(xb, 0, 1)
;     RES_ST(xa, 0, 0)
;     RES_LD(xa, 1, 0)
;     RES_ST(xb, 0, 1)
;     RES_LD(xb, 1, 1)
;     RES_ST(xa, 1, 0)
;     RES_ST(xb, 1, 1)
.Lmg_rnf_23:
	s_mul_i32 s12, s53, 9
	s_add_u32 s12, s12, s1
	s_mul_i32 s12, s12, 6144
	s_lshl_b32 s11, s11, 10
	s_add_u32 s12, s12, s11
	s_add_u32 s12, s12, s91
	s_lshl_b32 s12, s12, 2
	s_add_u32 s12, s12, 0x1d300000
	s_add_u32 s86, s24, s12
	s_addc_u32 s87, s25, 0
	v_lshlrev_b32_e32 v184, 2, v227
	global_load_dword v229, v184, s[86:87]
	global_load_dword v230, v184, s[86:87] offset:128
	v_lshl_add_u32 v185, v228, 2, s0
	v_lshlrev_b32_e32 v185, 10, v185
	v_add3_u32 v185, v185, s91, v227
	v_lshlrev_b32_e32 v231, 2, v185
	s_waitcnt lgkmcnt(0)
	s_waitcnt vmcnt(0)
	v_mov_b32_e32 v144, v231
	v_add_u32_e32 v145, 0x1000, v231
	v_add_u32_e32 v146, 0x2000, v231
	v_add_u32_e32 v147, 0x3000, v231
	v_add_u32_e32 v148, 0x8000, v231
	v_add_u32_e32 v149, 0x9000, v231
	v_add_u32_e32 v150, 0xa000, v231
	v_add_u32_e32 v151, 0xb000, v231
	v_add_u32_e32 v152, 0x10000, v231
	v_add_u32_e32 v153, 0x11000, v231
	v_add_u32_e32 v154, 0x12000, v231
	v_add_u32_e32 v155, 0x13000, v231
	v_add_u32_e32 v156, 0x18000, v231
	v_add_u32_e32 v157, 0x19000, v231
	v_add_u32_e32 v158, 0x1a000, v231
	v_add_u32_e32 v159, 0x1b000, v231
	v_mul_f32_e32 v0, v229, v0
	v_mul_f32_e32 v1, v229, v1
	v_mul_f32_e32 v2, v229, v2
	v_mul_f32_e32 v3, v229, v3
	v_mul_f32_e32 v4, v229, v4
	v_mul_f32_e32 v5, v229, v5
	v_mul_f32_e32 v6, v229, v6
	v_mul_f32_e32 v7, v229, v7
	v_mul_f32_e32 v8, v229, v8
	v_mul_f32_e32 v9, v229, v9
	v_mul_f32_e32 v10, v229, v10
	v_mul_f32_e32 v11, v229, v11
	v_mul_f32_e32 v12, v229, v12
	v_mul_f32_e32 v13, v229, v13
	v_mul_f32_e32 v14, v229, v14
	v_mul_f32_e32 v15, v229, v15
	global_atomic_add_f32 v144, v0, s[82:83]
	global_atomic_add_f32 v145, v1, s[82:83]
	global_atomic_add_f32 v146, v2, s[82:83]
	global_atomic_add_f32 v147, v3, s[82:83]
	global_atomic_add_f32 v148, v4, s[82:83]
	global_atomic_add_f32 v149, v5, s[82:83]
	global_atomic_add_f32 v150, v6, s[82:83]
	global_atomic_add_f32 v151, v7, s[82:83]
	global_atomic_add_f32 v152, v8, s[82:83]
	global_atomic_add_f32 v153, v9, s[82:83]
	global_atomic_add_f32 v154, v10, s[82:83]
	global_atomic_add_f32 v155, v11, s[82:83]
	global_atomic_add_f32 v156, v12, s[82:83]
	global_atomic_add_f32 v157, v13, s[82:83]
	global_atomic_add_f32 v158, v14, s[82:83]
	global_atomic_add_f32 v159, v15, s[82:83]
	v_mul_f32_e32 v16, v230, v16
	v_mul_f32_e32 v17, v230, v17
	v_mul_f32_e32 v18, v230, v18
	v_mul_f32_e32 v19, v230, v19
	v_mul_f32_e32 v20, v230, v20
	v_mul_f32_e32 v21, v230, v21
	v_mul_f32_e32 v22, v230, v22
	v_mul_f32_e32 v23, v230, v23
	v_mul_f32_e32 v24, v230, v24
	v_mul_f32_e32 v25, v230, v25
	v_mul_f32_e32 v26, v230, v26
	v_mul_f32_e32 v27, v230, v27
	v_mul_f32_e32 v28, v230, v28
	v_mul_f32_e32 v29, v230, v29
	v_mul_f32_e32 v30, v230, v30
	v_mul_f32_e32 v31, v230, v31
	global_atomic_add_f32 v144, v16, s[82:83] offset:128
	global_atomic_add_f32 v145, v17, s[82:83] offset:128
	global_atomic_add_f32 v146, v18, s[82:83] offset:128
	global_atomic_add_f32 v147, v19, s[82:83] offset:128
	global_atomic_add_f32 v148, v20, s[82:83] offset:128
	global_atomic_add_f32 v149, v21, s[82:83] offset:128
	global_atomic_add_f32 v150, v22, s[82:83] offset:128
	global_atomic_add_f32 v151, v23, s[82:83] offset:128
	global_atomic_add_f32 v152, v24, s[82:83] offset:128
	global_atomic_add_f32 v153, v25, s[82:83] offset:128
	global_atomic_add_f32 v154, v26, s[82:83] offset:128
	global_atomic_add_f32 v155, v27, s[82:83] offset:128
	global_atomic_add_f32 v156, v28, s[82:83] offset:128
	global_atomic_add_f32 v157, v29, s[82:83] offset:128
	global_atomic_add_f32 v158, v30, s[82:83] offset:128
	global_atomic_add_f32 v159, v31, s[82:83] offset:128
	v_add_u32_e32 v160, 0x20000, v231
	v_add_u32_e32 v161, 0x21000, v231
	v_add_u32_e32 v162, 0x22000, v231
	v_add_u32_e32 v163, 0x23000, v231
	v_add_u32_e32 v164, 0x28000, v231
	v_add_u32_e32 v165, 0x29000, v231
	v_add_u32_e32 v166, 0x2a000, v231
	v_add_u32_e32 v167, 0x2b000, v231
	v_add_u32_e32 v168, 0x30000, v231
	v_add_u32_e32 v169, 0x31000, v231
	v_add_u32_e32 v170, 0x32000, v231
	v_add_u32_e32 v171, 0x33000, v231
	v_add_u32_e32 v172, 0x38000, v231
	v_add_u32_e32 v173, 0x39000, v231
	v_add_u32_e32 v174, 0x3a000, v231
	v_add_u32_e32 v175, 0x3b000, v231
	v_mul_f32_e32 v32, v229, v32
	v_mul_f32_e32 v33, v229, v33
	v_mul_f32_e32 v34, v229, v34
	v_mul_f32_e32 v35, v229, v35
	v_mul_f32_e32 v36, v229, v36
	v_mul_f32_e32 v37, v229, v37
	v_mul_f32_e32 v38, v229, v38
	v_mul_f32_e32 v39, v229, v39
	v_mul_f32_e32 v40, v229, v40
	v_mul_f32_e32 v41, v229, v41
	v_mul_f32_e32 v42, v229, v42
	v_mul_f32_e32 v43, v229, v43
	v_mul_f32_e32 v44, v229, v44
	v_mul_f32_e32 v45, v229, v45
	v_mul_f32_e32 v46, v229, v46
	v_mul_f32_e32 v47, v229, v47
	global_atomic_add_f32 v160, v32, s[82:83]
	global_atomic_add_f32 v161, v33, s[82:83]
	global_atomic_add_f32 v162, v34, s[82:83]
	global_atomic_add_f32 v163, v35, s[82:83]
	global_atomic_add_f32 v164, v36, s[82:83]
	global_atomic_add_f32 v165, v37, s[82:83]
	global_atomic_add_f32 v166, v38, s[82:83]
	global_atomic_add_f32 v167, v39, s[82:83]
	global_atomic_add_f32 v168, v40, s[82:83]
	global_atomic_add_f32 v169, v41, s[82:83]
	global_atomic_add_f32 v170, v42, s[82:83]
	global_atomic_add_f32 v171, v43, s[82:83]
	global_atomic_add_f32 v172, v44, s[82:83]
	global_atomic_add_f32 v173, v45, s[82:83]
	global_atomic_add_f32 v174, v46, s[82:83]
	global_atomic_add_f32 v175, v47, s[82:83]
	v_mul_f32_e32 v48, v230, v48
	v_mul_f32_e32 v49, v230, v49
	v_mul_f32_e32 v50, v230, v50
	v_mul_f32_e32 v51, v230, v51
	v_mul_f32_e32 v52, v230, v52
	v_mul_f32_e32 v53, v230, v53
	v_mul_f32_e32 v54, v230, v54
	v_mul_f32_e32 v55, v230, v55
	v_mul_f32_e32 v56, v230, v56
	v_mul_f32_e32 v57, v230, v57
	v_mul_f32_e32 v58, v230, v58
; #define RES_LD(X, mi_, ni_) { _Pragma("unroll") for (int r = 0; r < 16; ++r) X[r] = xo_base[(size_t)((mi_) * 32 + crow(r, h)) * D + (ni_) * 32]; }
; #define RES_ST(X, mi_, ni_) { _Pragma("unroll") for (int r = 0; r < 16; ++r) xn_base[(size_t)((mi_) * 32 + crow(r, h)) * D + (ni_) * 32] = X[r] + gate[ni_] * acc[mi_][ni_][r]; }
; template <int EPI>
; DI void epilogue(const Params& p, int layer, f32x16 (&acc)[2][2], int mrow0, int ncol0, int lane) {
;     ...
;   } else if (EPI == EPI_RES1 || EPI == EPI_RES2) {
;     const float* mod = (const float*)(p.ws + OFF_MOD) + (size_t)layer * 9 * 6144;
;     const int b9 = mrow0 < NLAT ? (mrow0 >> 12) : 8;
;     const int gsel = (EPI == EPI_RES1) ? 2 : 5;
;     const bool first = (EPI == EPI_RES1) && layer == 0;
;     const float* xo_base = xold_ptr(p, layer, first, mrow0) + (ncol0 + c);
;     float* xn_base = xnew_ptr(p, mrow0) + (ncol0 + c);
;     float gate[2];
; #pragma unroll
;     for (int ni = 0; ni < 2; ++ni) gate[ni] = mod[b9 * 6144 + gsel * 1024 + ncol0 + ni * 32 + c];
;     float xa[16], xb[16];
;     ...
;     RES_LD(xa, 0, 0)
;     RES_LD(xb, 0, 1)
;     RES_ST(xa, 0, 0)
;     RES_LD(xa, 1, 0)
;     RES_ST(xb, 0, 1)
;     RES_LD(xb, 1, 1)
;     RES_ST(xa, 1, 0)
;     RES_ST(xb, 1, 1)
	v_mul_f32_e32 v59, v230, v59
	v_mul_f32_e32 v60, v230, v60
	v_mul_f32_e32 v61, v230, v61
	v_mul_f32_e32 v62, v230, v62
	v_mul_f32_e32 v63, v230, v63
	global_atomic_add_f32 v160, v48, s[82:83] offset:128
	global_atomic_add_f32 v161, v49, s[82:83] offset:128
	global_atomic_add_f32 v162, v50, s[82:83] offset:128
	global_atomic_add_f32 v163, v51, s[82:83] offset:128
	global_atomic_add_f32 v164, v52, s[82:83] offset:128
	global_atomic_add_f32 v165, v53, s[82:83] offset:128
	global_atomic_add_f32 v166, v54, s[82:83] offset:128
	global_atomic_add_f32 v167, v55, s[82:83] offset:128
	global_atomic_add_f32 v168, v56, s[82:83] offset:128
	global_atomic_add_f32 v169, v57, s[82:83] offset:128
	global_atomic_add_f32 v170, v58, s[82:83] offset:128
	global_atomic_add_f32 v171, v59, s[82:83] offset:128
	global_atomic_add_f32 v172, v60, s[82:83] offset:128
	global_atomic_add_f32 v173, v61, s[82:83] offset:128
	global_atomic_add_f32 v174, v62, s[82:83] offset:128
	global_atomic_add_f32 v175, v63, s[82:83] offset:128
	v_add_u32_e32 v144, 0x40000, v231
	v_add_u32_e32 v145, 0x41000, v231
	v_add_u32_e32 v146, 0x42000, v231
	v_add_u32_e32 v147, 0x43000, v231
	v_add_u32_e32 v148, 0x48000, v231
	v_add_u32_e32 v149, 0x49000, v231
	v_add_u32_e32 v150, 0x4a000, v231
	v_add_u32_e32 v151, 0x4b000, v231
	v_add_u32_e32 v152, 0x50000, v231
	v_add_u32_e32 v153, 0x51000, v231
	v_add_u32_e32 v154, 0x52000, v231
	v_add_u32_e32 v155, 0x53000, v231
	v_add_u32_e32 v156, 0x58000, v231
	v_add_u32_e32 v157, 0x59000, v231
	v_add_u32_e32 v158, 0x5a000, v231
	v_add_u32_e32 v159, 0x5b000, v231
	v_mul_f32_e32 v64, v229, v64
	v_mul_f32_e32 v65, v229, v65
	v_mul_f32_e32 v66, v229, v66
	v_mul_f32_e32 v67, v229, v67
	v_mul_f32_e32 v68, v229, v68
	v_mul_f32_e32 v69, v229, v69
	v_mul_f32_e32 v70, v229, v70
	v_mul_f32_e32 v71, v229, v71
	v_mul_f32_e32 v72, v229, v72
	v_mul_f32_e32 v73, v229, v73
	v_mul_f32_e32 v74, v229, v74
	v_mul_f32_e32 v75, v229, v75
	v_mul_f32_e32 v76, v229, v76
	v_mul_f32_e32 v77, v229, v77
	v_mul_f32_e32 v78, v229, v78
	v_mul_f32_e32 v79, v229, v79
	global_atomic_add_f32 v144, v64, s[82:83]
	global_atomic_add_f32 v145, v65, s[82:83]
	global_atomic_add_f32 v146, v66, s[82:83]
	global_atomic_add_f32 v147, v67, s[82:83]
	global_atomic_add_f32 v148, v68, s[82:83]
	global_atomic_add_f32 v149, v69, s[82:83]
	global_atomic_add_f32 v150, v70, s[82:83]
	global_atomic_add_f32 v151, v71, s[82:83]
	global_atomic_add_f32 v152, v72, s[82:83]
	global_atomic_add_f32 v153, v73, s[82:83]
	global_atomic_add_f32 v154, v74, s[82:83]
	global_atomic_add_f32 v155, v75, s[82:83]
	global_atomic_add_f32 v156, v76, s[82:83]
	global_atomic_add_f32 v157, v77, s[82:83]
	global_atomic_add_f32 v158, v78, s[82:83]
	global_atomic_add_f32 v159, v79, s[82:83]
	v_mul_f32_e32 v80, v230, v80
	v_mul_f32_e32 v81, v230, v81
	v_mul_f32_e32 v82, v230, v82
	v_mul_f32_e32 v83, v230, v83
	v_mul_f32_e32 v84, v230, v84
	v_mul_f32_e32 v85, v230, v85
	v_mul_f32_e32 v86, v230, v86
	v_mul_f32_e32 v87, v230, v87
	v_mul_f32_e32 v88, v230, v88
	v_mul_f32_e32 v89, v230, v89
	v_mul_f32_e32 v90, v230, v90
	v_mul_f32_e32 v91, v230, v91
	v_mul_f32_e32 v92, v230, v92
	v_mul_f32_e32 v93, v230, v93
	v_mul_f32_e32 v94, v230, v94
	v_mul_f32_e32 v95, v230, v95
	global_atomic_add_f32 v144, v80, s[82:83] offset:128
	global_atomic_add_f32 v145, v81, s[82:83] offset:128
	global_atomic_add_f32 v146, v82, s[82:83] offset:128
	global_atomic_add_f32 v147, v83, s[82:83] offset:128
	global_atomic_add_f32 v148, v84, s[82:83] offset:128
	global_atomic_add_f32 v149, v85, s[82:83] offset:128
	global_atomic_add_f32 v150, v86, s[82:83] offset:128
	global_atomic_add_f32 v151, v87, s[82:83] offset:128
; #define RES_LD(X, mi_, ni_) { _Pragma("unroll") for (int r = 0; r < 16; ++r) X[r] = xo_base[(size_t)((mi_) * 32 + crow(r, h)) * D + (ni_) * 32]; }
; #define RES_ST(X, mi_, ni_) { _Pragma("unroll") for (int r = 0; r < 16; ++r) xn_base[(size_t)((mi_) * 32 + crow(r, h)) * D + (ni_) * 32] = X[r] + gate[ni_] * acc[mi_][ni_][r]; }
; template <int EPI>
; DI void epilogue(const Params& p, int layer, f32x16 (&acc)[2][2], int mrow0, int ncol0, int lane) {
;     ...
;   } else if (EPI == EPI_RES1 || EPI == EPI_RES2) {
;     const float* mod = (const float*)(p.ws + OFF_MOD) + (size_t)layer * 9 * 6144;
;     const int b9 = mrow0 < NLAT ? (mrow0 >> 12) : 8;
;     const int gsel = (EPI == EPI_RES1) ? 2 : 5;
;     const bool first = (EPI == EPI_RES1) && layer == 0;
;     const float* xo_base = xold_ptr(p, layer, first, mrow0) + (ncol0 + c);
;     float* xn_base = xnew_ptr(p, mrow0) + (ncol0 + c);
;     float gate[2];
; #pragma unroll
;     for (int ni = 0; ni < 2; ++ni) gate[ni] = mod[b9 * 6144 + gsel * 1024 + ncol0 + ni * 32 + c];
;     float xa[16], xb[16];
;     ...
;     RES_LD(xa, 0, 0)
;     RES_LD(xb, 0, 1)
;     RES_ST(xa, 0, 0)
;     RES_LD(xa, 1, 0)
;     RES_ST(xb, 0, 1)
;     RES_LD(xb, 1, 1)
;     RES_ST(xa, 1, 0)
;     RES_ST(xb, 1, 1)
	global_atomic_add_f32 v152, v88, s[82:83] offset:128
	global_atomic_add_f32 v153, v89, s[82:83] offset:128
	global_atomic_add_f32 v154, v90, s[82:83] offset:128
	global_atomic_add_f32 v155, v91, s[82:83] offset:128
	global_atomic_add_f32 v156, v92, s[82:83] offset:128
	global_atomic_add_f32 v157, v93, s[82:83] offset:128
	global_atomic_add_f32 v158, v94, s[82:83] offset:128
	global_atomic_add_f32 v159, v95, s[82:83] offset:128
	v_add_u32_e32 v160, 0x60000, v231
	v_add_u32_e32 v161, 0x61000, v231
	v_add_u32_e32 v162, 0x62000, v231
	v_add_u32_e32 v163, 0x63000, v231
	v_add_u32_e32 v164, 0x68000, v231
	v_add_u32_e32 v165, 0x69000, v231
	v_add_u32_e32 v166, 0x6a000, v231
	v_add_u32_e32 v167, 0x6b000, v231
	v_add_u32_e32 v168, 0x70000, v231
	v_add_u32_e32 v169, 0x71000, v231
	v_add_u32_e32 v170, 0x72000, v231
	v_add_u32_e32 v171, 0x73000, v231
	v_add_u32_e32 v172, 0x78000, v231
	v_add_u32_e32 v173, 0x79000, v231
	v_add_u32_e32 v174, 0x7a000, v231
	v_add_u32_e32 v175, 0x7b000, v231
	v_mul_f32_e32 v96, v229, v96
	v_mul_f32_e32 v97, v229, v97
	v_mul_f32_e32 v98, v229, v98
	v_mul_f32_e32 v99, v229, v99
	v_mul_f32_e32 v100, v229, v100
	v_mul_f32_e32 v101, v229, v101
	v_mul_f32_e32 v102, v229, v102
	v_mul_f32_e32 v103, v229, v103
	v_mul_f32_e32 v104, v229, v104
	v_mul_f32_e32 v105, v229, v105
	v_mul_f32_e32 v106, v229, v106
	v_mul_f32_e32 v107, v229, v107
	v_mul_f32_e32 v108, v229, v108
	v_mul_f32_e32 v109, v229, v109
	v_mul_f32_e32 v110, v229, v110
	v_mul_f32_e32 v111, v229, v111
	global_atomic_add_f32 v160, v96, s[82:83]
	global_atomic_add_f32 v161, v97, s[82:83]
	global_atomic_add_f32 v162, v98, s[82:83]
	global_atomic_add_f32 v163, v99, s[82:83]
	global_atomic_add_f32 v164, v100, s[82:83]
	global_atomic_add_f32 v165, v101, s[82:83]
	global_atomic_add_f32 v166, v102, s[82:83]
	global_atomic_add_f32 v167, v103, s[82:83]
	global_atomic_add_f32 v168, v104, s[82:83]
	global_atomic_add_f32 v169, v105, s[82:83]
	global_atomic_add_f32 v170, v106, s[82:83]
	global_atomic_add_f32 v171, v107, s[82:83]
	global_atomic_add_f32 v172, v108, s[82:83]
	global_atomic_add_f32 v173, v109, s[82:83]
	global_atomic_add_f32 v174, v110, s[82:83]
	global_atomic_add_f32 v175, v111, s[82:83]
	v_mul_f32_e32 v112, v230, v112
	v_mul_f32_e32 v113, v230, v113
	v_mul_f32_e32 v114, v230, v114
	v_mul_f32_e32 v115, v230, v115
	v_mul_f32_e32 v116, v230, v116
	v_mul_f32_e32 v117, v230, v117
	v_mul_f32_e32 v118, v230, v118
	v_mul_f32_e32 v119, v230, v119
	v_mul_f32_e32 v120, v230, v120
	v_mul_f32_e32 v121, v230, v121
	v_mul_f32_e32 v122, v230, v122
	v_mul_f32_e32 v123, v230, v123
	v_mul_f32_e32 v124, v230, v124
	v_mul_f32_e32 v125, v230, v125
	v_mul_f32_e32 v126, v230, v126
	v_mul_f32_e32 v127, v230, v127
	global_atomic_add_f32 v160, v112, s[82:83] offset:128
	global_atomic_add_f32 v161, v113, s[82:83] offset:128
	global_atomic_add_f32 v162, v114, s[82:83] offset:128
	global_atomic_add_f32 v163, v115, s[82:83] offset:128
	global_atomic_add_f32 v164, v116, s[82:83] offset:128
	global_atomic_add_f32 v165, v117, s[82:83] offset:128
	global_atomic_add_f32 v166, v118, s[82:83] offset:128
	global_atomic_add_f32 v167, v119, s[82:83] offset:128
	global_atomic_add_f32 v168, v120, s[82:83] offset:128
	global_atomic_add_f32 v169, v121, s[82:83] offset:128
	global_atomic_add_f32 v170, v122, s[82:83] offset:128
	global_atomic_add_f32 v171, v123, s[82:83] offset:128
	global_atomic_add_f32 v172, v124, s[82:83] offset:128
	global_atomic_add_f32 v173, v125, s[82:83] offset:128
	global_atomic_add_f32 v174, v126, s[82:83] offset:128
	global_atomic_add_f32 v175, v127, s[82:83] offset:128
	s_branch .Lmg_next
